# v15 + attention: workgroups 0-63 run their sample-group unit first and the prompt unit second (de-synchronises the prompt-unit load bursts)
# speedup vs baseline: 1.0062x; 1.0062x over previous
; #define LAS __attribute__((address_space(3)))
; #define LAS __attribute__((address_space(3)))
; __device__ __forceinline__ unsigned pk2(float lo, float hi) { return pg8::cvt_pk_bf16(lo, hi); }
; template <bool DO_SWA, bool DO_MEM>
; __device__ __forceinline__ void attn_unit(const Args& a, unsigned char* ws, LAS unsigned char* lds, int l, int tid_in, int lane_in, int wave, int unit) {
;     ...
;             const float tot = red_m[qs * 16 + fr] + red_m[64 + qs * 16 + fr];
;             const float rs = 1.0f / sqrtf(tot * (1.0f / 256.0f) + EPS);
; #pragma unroll
;             for (int hp = 0; hp < 2; ++hp)
; #pragma unroll
;                 for (int dt = 0; dt < 4; ++dt) {
;                     const f32x4 o = omem[hp][dt] * rs;
;                     v2u w; w.x = pk2(o[0], o[1]); w.y = pk2(o[2], o[3]);
;                     *(v2u*)(MIX + qrow * D + 768 + (hp * 2 + g) * 64 + dt * 16 + 4 * fq) = w;
;                 }
;             __syncthreads();
; __device__ __forceinline__ void attn_phase(const Args& a, unsigned char* ws, LAS unsigned char* lds, int l, int tid_in, int lane_in, int wave) {
;     for (int unit0 = blockIdx.x; unit0 < NUNITS + 32; unit0 += gridDim.x) {
;         if (unit0 < 256) attn_unit<true, true>(a, ws, lds, l, tid_in, lane_in, wave, (unit0 & 7) * 32 + (unit0 >> 3));
;         else if (unit0 < 288) attn_unit<true, false>(a, ws, lds, l, tid_in, lane_in, wave, unit0);
;         else attn_unit<false, true>(a, ws, lds, l, tid_in, lane_in, wave, unit0 - 32);
;     }
.LBB0_251:
	s_and_b64 vcc, exec, s[0:1]
	s_cbranch_vccz .LBB0_443
	v_readlane_b32 s0, v255, 21
	s_cmp_gt_i32 s0, 0
	s_mov_b64 s[0:1], -1
	s_cbranch_scc0 .LBB0_441
	v_readlane_b32 s0, v251, 19
	v_readlane_b32 s1, v251, 20
	s_andn2_b64 vcc, exec, s[0:1]
	s_cbranch_vccnz .LBB0_294
	s_add_u32 s7, s48, 0x8800000
	s_addc_u32 s24, s49, 0
	s_add_u32 s26, s48, 0x9c00000
	s_addc_u32 s27, s49, 0
	s_add_u32 s38, s48, 0xbd00000
	s_addc_u32 s39, s49, 0
	s_add_u32 s16, s48, 0xb800000
	s_addc_u32 s17, s49, 0
	s_add_u32 s28, s48, 0xb000000
	s_addc_u32 s29, s49, 0
	s_add_u32 s30, s48, 0xb400000
	v_readlane_b32 s0, v255, 19
	s_addc_u32 s31, s49, 0
	s_mov_b32 s2, s0
	s_add_u32 s20, s48, 0xef00000
	v_readlane_b32 s1, v255, 20
	s_mul_i32 s25, s0, 40
	s_addc_u32 s21, s49, 0
	s_lshl_b32 s41, s0, 5
	s_mulk_i32 s0, 0x300
	s_lshl_b32 s2, s2, 3
	v_readlane_b32 s3, v251, 27
	s_mov_b64 s[94:95], s[54:55]
	s_ashr_i32 s1, s0, 31
	s_add_i32 s2, s2, s3
	s_mov_b64 s[92:93], s[52:53]
	v_readlane_b32 s44, v252, 3
	s_ashr_i32 s3, s2, 31
	s_lshl_b64 s[0:1], s[0:1], 2
	v_readlane_b32 s54, v252, 13
	v_readlane_b32 s55, v252, 14
	s_add_u32 s10, s54, s0
	v_readlane_b32 s52, v252, 11
	s_addc_u32 s11, s55, s1
	s_lshl_b64 s[0:1], s[2:3], 2
	v_readlane_b32 s48, v252, 7
	v_readlane_b32 s49, v252, 8
	v_readlane_b32 s53, v252, 12
	s_add_u32 s12, s52, s0
	v_readlane_b32 s56, v252, 15
	v_readlane_b32 s57, v252, 16
	v_readlane_b32 s58, v252, 17
	v_readlane_b32 s59, v252, 18
	v_readlane_b32 s48, v255, 23
	s_addc_u32 s13, s53, s1
	s_load_dwordx2 s[98:99], s[12:13], 0x0
	s_load_dwordx2 s[100:101], s[12:13], 0x8
	s_mov_b64 s[52:53], s[92:93]
	v_readlane_b32 s49, v255, 24
	v_readlane_b32 s57, v255, 15
	v_readlane_b32 s56, v255, 14
	v_readlane_b32 s59, v255, 10
	v_readlane_b32 s58, v255, 9
	s_mov_b64 s[54:55], s[94:95]
	s_add_i32 s40, s25, 0xfffffee8
	s_addk_i32 s41, 0xff00
	v_readlane_b32 s92, v254, 49
	v_readlane_b32 s93, v254, 29
	v_readlane_b32 s94, v251, 0
	v_readlane_b32 s45, v252, 4
	v_readlane_b32 s46, v252, 5
	v_readlane_b32 s47, v252, 6
	v_readlane_b32 s50, v252, 9
	v_readlane_b32 s51, v252, 10
	s_waitcnt lgkmcnt(0)
	s_mov_b32 s32, 0
	s_cmp_lt_u32 s94, 64
	s_cbranch_scc0 .Latt_ord0
	s_mov_b32 s32, 1
	v_readlane_b32 s0, v254, 32
	s_nop 0
	s_add_i32 s93, s93, s0
	v_readlane_b32 s0, v254, 33
	s_add_i32 s94, s94, s58
	s_add_i32 s92, s92, s0
.Latt_ord0:
	s_branch .LBB0_257
.LBB0_255:
	s_or_b64 exec, exec, s[0:1]
	s_add_i32 s0, 0, 0x22a00
	v_lshl_add_u32 v4, v211, 2, s0
	s_waitcnt lgkmcnt(0)
	v_lshl_add_u32 v5, v143, 2, s0
	s_barrier
	ds_read_b32 v4, v4
	ds_read_b32 v5, v5
	s_mov_b32 s0, 0xf800000
	s_mov_b32 s43, s35
	s_waitcnt lgkmcnt(0)
	v_add_f32_e32 v4, v4, v5
	v_fmamk_f32 v4, v4, 0x3b800000, v218
	v_mul_f32_e32 v5, 0x4f800000, v4
	v_cmp_gt_f32_e32 vcc, s0, v4
	s_nop 1
	v_cndmask_b32_e32 v4, v4, v5, vcc
	v_sqrt_f32_e32 v5, v4
	s_nop 0
	v_add_u32_e32 v6, -1, v5
	v_fma_f32 v7, -v6, v5, v4
	v_cmp_ge_f32_e64 s[0:1], 0, v7
	v_add_u32_e32 v7, 1, v5
	s_nop 0
	v_cndmask_b32_e64 v6, v5, v6, s[0:1]
	v_fma_f32 v5, -v7, v5, v4
	v_cmp_lt_f32_e64 s[0:1], 0, v5
	s_nop 1
	v_cndmask_b32_e64 v5, v6, v7, s[0:1]
	v_mul_f32_e32 v6, 0x37800000, v5
	v_cndmask_b32_e32 v5, v5, v6, vcc
	v_cmp_class_f32_e32 vcc, v4, v219
	s_nop 1
	v_cndmask_b32_e32 v4, v5, v4, vcc
	v_div_scale_f32 v5, s[0:1], v4, v4, 1.0
	v_rcp_f32_e32 v6, v5
	s_nop 0
	v_fma_f32 v7, -v5, v6, 1.0
	v_fmac_f32_e32 v6, v7, v6
	v_div_scale_f32 v7, vcc, 1.0, v4, 1.0
	v_mul_f32_e32 v8, v7, v6
	v_fma_f32 v9, -v5, v8, v7
	v_fmac_f32_e32 v8, v9, v6
	v_fma_f32 v5, -v5, v8, v7
	v_div_fmas_f32 v5, v5, v6, v8
	v_div_fixup_f32 v4, v5, v4, 1.0
	v_pk_mul_f32 v[10:11], v[106:107], v[4:5] op_sel_hi:[1,0]
	v_lshl_add_u64 v[6:7], v[140:141], 0, s[42:43]
	v_pk_mul_f32 v[8:9], v[104:105], v[4:5] op_sel_hi:[1,0]
	v_cvt_pk_bf16_f32 v10, v10, v11
	v_pk_mul_f32 v[2:3], v[2:3], v[4:5] op_sel_hi:[1,0]
	v_cvt_pk_bf16_f32 v11, v8, v9
	global_store_dwordx2 v[6:7], v[10:11], off offset:1536
	v_pk_mul_f32 v[10:11], v[110:111], v[4:5] op_sel_hi:[1,0]
	v_pk_mul_f32 v[8:9], v[108:109], v[4:5] op_sel_hi:[1,0]
	v_cvt_pk_bf16_f32 v10, v10, v11
	v_pk_mul_f32 v[0:1], v[0:1], v[4:5] op_sel_hi:[1,0]
	v_cvt_pk_bf16_f32 v11, v8, v9
	global_store_dwordx2 v[6:7], v[10:11], off offset:1568
	v_pk_mul_f32 v[10:11], v[114:115], v[4:5] op_sel_hi:[1,0]
	v_pk_mul_f32 v[8:9], v[112:113], v[4:5] op_sel_hi:[1,0]
	v_cvt_pk_bf16_f32 v10, v10, v11
	s_nop 0
	v_cvt_pk_bf16_f32 v11, v8, v9
	global_store_dwordx2 v[6:7], v[10:11], off offset:1600
	v_pk_mul_f32 v[10:11], v[82:83], v[4:5] op_sel_hi:[1,0]
	v_pk_mul_f32 v[8:9], v[80:81], v[4:5] op_sel_hi:[1,0]
	v_cvt_pk_bf16_f32 v10, v10, v11
	s_nop 0
	v_cvt_pk_bf16_f32 v11, v8, v9
	global_store_dwordx2 v[6:7], v[10:11], off offset:1632
	v_pk_mul_f32 v[10:11], v[34:35], v[4:5] op_sel_hi:[1,0]
	v_pk_mul_f32 v[8:9], v[32:33], v[4:5] op_sel_hi:[1,0]
	v_cvt_pk_bf16_f32 v10, v10, v11
	s_nop 0
	v_cvt_pk_bf16_f32 v11, v8, v9
	global_store_dwordx2 v[6:7], v[10:11], off offset:1792
	v_pk_mul_f32 v[10:11], v[40:41], v[4:5] op_sel_hi:[1,0]
	v_pk_mul_f32 v[8:9], v[38:39], v[4:5] op_sel_hi:[1,0]
	v_cvt_pk_bf16_f32 v10, v10, v11
	s_nop 0
	v_cvt_pk_bf16_f32 v11, v8, v9
	global_store_dwordx2 v[6:7], v[10:11], off offset:1824
	v_pk_mul_f32 v[10:11], v[44:45], v[4:5] op_sel_hi:[1,0]
	v_pk_mul_f32 v[8:9], v[42:43], v[4:5] op_sel_hi:[1,0]
	v_cvt_pk_bf16_f32 v10, v10, v11
	s_nop 0
	v_cvt_pk_bf16_f32 v11, v8, v9
	global_store_dwordx2 v[6:7], v[10:11], off offset:1856
	v_cvt_pk_bf16_f32 v2, v2, v3
	v_cvt_pk_bf16_f32 v3, v0, v1
	global_store_dwordx2 v[6:7], v[2:3], off offset:1888
	s_barrier
.LBB0_256:
	s_cmp_eq_u32 s32, 0
	s_cbranch_scc1 .Latt_norm
	s_cmp_eq_u32 s32, 2
	s_cbranch_scc1 .Latt_done
	s_mov_b32 s32, 2
	v_readlane_b32 s0, v254, 32
	s_nop 0
	s_sub_i32 s93, s93, s0
	v_readlane_b32 s0, v254, 33
	s_sub_i32 s94, s94, s58
	s_sub_i32 s92, s92, s0
	s_branch .LBB0_257
.Latt_done:
	s_mov_b32 s32, 0
	s_branch .LBB0_294
